# P2 standard K-loop: back edge rotated (trip-counter and next-tile pointer SALU moved ahead of the closing barrier)
# speedup vs baseline: 1.0056x; 1.0056x over previous
.Lp2_rot:
	s_add_i32 s47, 0, 0x10000
	v_add_u32_e32 v164, s47, v158
	ds_read_b128 v[160:163], v164
	ds_read_b128 v[176:179], v164 offset:1024
	ds_read_b128 v[180:183], v164 offset:2048
	ds_read_b128 v[184:187], v164 offset:3072
	s_cmp_eq_u32 s38, s20
	s_cselect_b32 s20, s8, s22
	s_cselect_b32 s21, s9, s21
	s_cselect_b32 s23, s11, s45
	s_cselect_b32 s22, s10, s44
	v_lshl_add_u64 v[164:165], s[18:19], 0, v[156:157]
	s_add_i32 m0, s29, 0xc000
	ds_read_b128 v[188:191], v159
	ds_read_b128 v[192:195], v159 offset:1024
	ds_read_b128 v[196:199], v159 offset:2048
	ds_read_b128 v[200:203], v159 offset:3072
	ds_read_b128 v[204:207], v159 offset:4096
	ds_read_b128 v[218:221], v159 offset:5120
	ds_read_b128 v[224:227], v159 offset:6144
	ds_read_b128 v[228:231], v159 offset:7168
	global_load_lds_dwordx4 v[164:165], off
	v_lshl_add_u64 v[164:165], s[18:19], 0, v[154:155]
	s_add_i32 m0, s29, 0xe000
	s_nop 0
	global_load_lds_dwordx4 v[164:165], off
	s_waitcnt lgkmcnt(8)
	s_waitcnt vmcnt(10)
	s_barrier
	s_waitcnt lgkmcnt(0)
	s_setprio 1
	s_waitcnt lgkmcnt(0)
	v_mfma_f32_16x16x32_bf16 v[124:127], v[160:163], v[188:191], v[124:127]
	v_mfma_f32_16x16x32_bf16 v[128:131], v[180:183], v[188:191], v[128:131]
	v_mfma_f32_16x16x32_bf16 v[112:115], v[160:163], v[196:199], v[112:115]
	v_mfma_f32_16x16x32_bf16 v[108:111], v[180:183], v[196:199], v[108:111]
	v_mfma_f32_16x16x32_bf16 v[96:99], v[160:163], v[204:207], v[96:99]
	v_mfma_f32_16x16x32_bf16 v[92:95], v[180:183], v[204:207], v[92:95]
	v_mfma_f32_16x16x32_bf16 v[76:79], v[160:163], v[224:227], v[76:79]
	v_mfma_f32_16x16x32_bf16 v[72:75], v[180:183], v[224:227], v[72:75]
	v_mfma_f32_16x16x32_bf16 v[124:127], v[176:179], v[192:195], v[124:127]
	v_mfma_f32_16x16x32_bf16 v[128:131], v[184:187], v[192:195], v[128:131]
	v_mfma_f32_16x16x32_bf16 v[112:115], v[176:179], v[200:203], v[112:115]
	v_mfma_f32_16x16x32_bf16 v[108:111], v[184:187], v[200:203], v[108:111]
	v_mfma_f32_16x16x32_bf16 v[96:99], v[176:179], v[218:221], v[96:99]
	v_mfma_f32_16x16x32_bf16 v[92:95], v[184:187], v[218:221], v[92:95]
	v_mfma_f32_16x16x32_bf16 v[76:79], v[176:179], v[228:231], v[76:79]
	v_mfma_f32_16x16x32_bf16 v[72:75], v[184:187], v[228:231], v[72:75]
	s_setprio 0
	s_barrier
	s_add_i32 s48, 0, 0x14000
	v_add_u32_e32 v164, s48, v158
	s_add_i32 s47, s47, s28
	ds_read_b128 v[232:235], v164
	ds_read_b128 v[236:239], v164 offset:1024
	ds_read_b128 v[240:243], v164 offset:2048
	ds_read_b128 v[244:247], v164 offset:3072
	v_lshl_add_u64 v[164:165], s[22:23], 0, v[166:167]
	s_mov_b32 m0, s47
	v_lshl_add_u64 v[248:249], s[22:23], 0, v[132:133]
	global_load_lds_dwordx4 v[164:165], off
	s_add_i32 m0, s47, 0x2000
	s_nop 0
	global_load_lds_dwordx4 v[248:249], off
	s_waitcnt vmcnt(10)
	s_barrier
	s_waitcnt lgkmcnt(0)
	s_setprio 1
	s_waitcnt lgkmcnt(0)
	v_mfma_f32_16x16x32_bf16 v[120:123], v[232:235], v[188:191], v[120:123]
	v_mfma_f32_16x16x32_bf16 v[116:119], v[240:243], v[188:191], v[116:119]
	v_mfma_f32_16x16x32_bf16 v[104:107], v[232:235], v[196:199], v[104:107]
	v_mfma_f32_16x16x32_bf16 v[100:103], v[240:243], v[196:199], v[100:103]
	v_mfma_f32_16x16x32_bf16 v[88:91], v[232:235], v[204:207], v[88:91]
	v_mfma_f32_16x16x32_bf16 v[84:87], v[240:243], v[204:207], v[84:87]
	v_mfma_f32_16x16x32_bf16 v[68:71], v[232:235], v[224:227], v[68:71]
	v_mfma_f32_16x16x32_bf16 v[64:67], v[240:243], v[224:227], v[64:67]
	v_mfma_f32_16x16x32_bf16 v[120:123], v[236:239], v[192:195], v[120:123]
	v_mfma_f32_16x16x32_bf16 v[116:119], v[244:247], v[192:195], v[116:119]
	v_mfma_f32_16x16x32_bf16 v[104:107], v[236:239], v[200:203], v[104:107]
	v_mfma_f32_16x16x32_bf16 v[100:103], v[244:247], v[200:203], v[100:103]
	v_mfma_f32_16x16x32_bf16 v[88:91], v[236:239], v[218:221], v[88:91]
	v_mfma_f32_16x16x32_bf16 v[84:87], v[244:247], v[218:221], v[84:87]
	v_mfma_f32_16x16x32_bf16 v[68:71], v[236:239], v[228:231], v[68:71]
	v_mfma_f32_16x16x32_bf16 v[64:67], v[244:247], v[228:231], v[64:67]
	s_setprio 0
	s_mov_b32 m0, s29
	v_lshl_add_u64 v[250:251], s[20:21], 0, v[136:137]
	s_barrier
	ds_read_b128 v[188:191], v159 offset:16384
	ds_read_b128 v[192:195], v159 offset:17408
	ds_read_b128 v[196:199], v159 offset:18432
	ds_read_b128 v[200:203], v159 offset:19456
	ds_read_b128 v[204:207], v159 offset:20480
	ds_read_b128 v[218:221], v159 offset:21504
	ds_read_b128 v[224:227], v159 offset:22528
	ds_read_b128 v[228:231], v159 offset:23552
	global_load_lds_dwordx4 v[250:251], off
	v_lshl_add_u64 v[210:211], s[20:21], 0, v[134:135]
	s_mov_b32 m0, s30
	s_nop 0
	global_load_lds_dwordx4 v[210:211], off
	s_barrier
	s_waitcnt lgkmcnt(0)
	s_setprio 1
	s_waitcnt lgkmcnt(0)
	v_mfma_f32_16x16x32_bf16 v[60:63], v[160:163], v[188:191], v[60:63]
	v_mfma_f32_16x16x32_bf16 v[56:59], v[180:183], v[188:191], v[56:59]
	v_mfma_f32_16x16x32_bf16 v[44:47], v[160:163], v[196:199], v[44:47]
	v_mfma_f32_16x16x32_bf16 v[40:43], v[180:183], v[196:199], v[40:43]
	v_mfma_f32_16x16x32_bf16 v[28:31], v[160:163], v[204:207], v[28:31]
	v_mfma_f32_16x16x32_bf16 v[24:27], v[180:183], v[204:207], v[24:27]
	v_mfma_f32_16x16x32_bf16 v[12:15], v[160:163], v[224:227], v[12:15]
	v_mfma_f32_16x16x32_bf16 v[8:11], v[180:183], v[224:227], v[8:11]
	v_mfma_f32_16x16x32_bf16 v[60:63], v[176:179], v[192:195], v[60:63]
	v_mfma_f32_16x16x32_bf16 v[56:59], v[184:187], v[192:195], v[56:59]
	v_mfma_f32_16x16x32_bf16 v[44:47], v[176:179], v[200:203], v[44:47]
	v_mfma_f32_16x16x32_bf16 v[40:43], v[184:187], v[200:203], v[40:43]
	v_mfma_f32_16x16x32_bf16 v[28:31], v[176:179], v[218:221], v[28:31]
	v_mfma_f32_16x16x32_bf16 v[24:27], v[184:187], v[218:221], v[24:27]
	v_mfma_f32_16x16x32_bf16 v[12:15], v[176:179], v[228:231], v[12:15]
	v_mfma_f32_16x16x32_bf16 v[8:11], v[184:187], v[228:231], v[8:11]
	s_setprio 0
	s_barrier
	s_add_u32 s22, s22, s12
	s_addc_u32 s23, s23, s13
	s_add_i32 s47, s48, s28
	v_lshl_add_u64 v[170:171], s[22:23], 0, v[166:167]
	s_mov_b32 m0, s47
	v_lshl_add_u64 v[172:173], s[22:23], 0, v[132:133]
	global_load_lds_dwordx4 v[170:171], off
	s_add_i32 m0, s47, 0x2000
	s_nop 0
	global_load_lds_dwordx4 v[172:173], off
	s_waitcnt vmcnt(10)
	s_barrier
	s_setprio 1
	v_mfma_f32_16x16x32_bf16 v[52:55], v[232:235], v[188:191], v[52:55]
	v_mfma_f32_16x16x32_bf16 v[48:51], v[240:243], v[188:191], v[48:51]
	v_mfma_f32_16x16x32_bf16 v[36:39], v[232:235], v[196:199], v[36:39]
	v_mfma_f32_16x16x32_bf16 v[32:35], v[240:243], v[196:199], v[32:35]
	v_mfma_f32_16x16x32_bf16 v[20:23], v[232:235], v[204:207], v[20:23]
	v_mfma_f32_16x16x32_bf16 v[16:19], v[240:243], v[204:207], v[16:19]
	v_mfma_f32_16x16x32_bf16 v[4:7], v[232:235], v[224:227], v[4:7]
	v_mfma_f32_16x16x32_bf16 v[0:3], v[240:243], v[224:227], v[0:3]
	v_mfma_f32_16x16x32_bf16 v[52:55], v[236:239], v[192:195], v[52:55]
	v_mfma_f32_16x16x32_bf16 v[48:51], v[244:247], v[192:195], v[48:51]
	v_mfma_f32_16x16x32_bf16 v[36:39], v[236:239], v[200:203], v[36:39]
	v_mfma_f32_16x16x32_bf16 v[32:35], v[244:247], v[200:203], v[32:35]
	v_mfma_f32_16x16x32_bf16 v[20:23], v[236:239], v[218:221], v[20:23]
	v_mfma_f32_16x16x32_bf16 v[16:19], v[244:247], v[218:221], v[16:19]
	v_mfma_f32_16x16x32_bf16 v[4:7], v[236:239], v[228:231], v[4:7]
	v_mfma_f32_16x16x32_bf16 v[0:3], v[244:247], v[228:231], v[0:3]
	s_setprio 0
	s_add_i32 s22, 0, 0x18000
	v_add_u32_e32 v169, s22, v158
	s_barrier
	ds_read_b128 v[160:163], v169
	ds_read_b128 v[176:179], v169 offset:1024
	ds_read_b128 v[180:183], v169 offset:2048
	ds_read_b128 v[184:187], v169 offset:3072
	s_add_u32 s20, s20, s12
	s_addc_u32 s21, s21, s13
	s_mov_b32 m0, s31
	v_lshl_add_u64 v[232:233], s[20:21], 0, v[136:137]
	ds_read_b128 v[188:191], v159 offset:32768
	ds_read_b128 v[192:195], v159 offset:33792
	ds_read_b128 v[196:199], v159 offset:34816
	ds_read_b128 v[200:203], v159 offset:35840
	ds_read_b128 v[204:207], v159 offset:36864
	ds_read_b128 v[218:221], v159 offset:37888
	ds_read_b128 v[224:227], v159 offset:38912
	ds_read_b128 v[228:231], v159 offset:39936
	global_load_lds_dwordx4 v[232:233], off
	v_lshl_add_u64 v[232:233], s[20:21], 0, v[134:135]
	s_mov_b32 m0, s34
	s_nop 0
	global_load_lds_dwordx4 v[232:233], off
	s_waitcnt lgkmcnt(8)
	s_waitcnt vmcnt(10)
	s_barrier
	s_waitcnt lgkmcnt(0)
	s_setprio 1
	s_waitcnt lgkmcnt(0)
	v_mfma_f32_16x16x32_bf16 v[124:127], v[160:163], v[188:191], v[124:127]
	v_mfma_f32_16x16x32_bf16 v[128:131], v[180:183], v[188:191], v[128:131]
	v_mfma_f32_16x16x32_bf16 v[112:115], v[160:163], v[196:199], v[112:115]
	v_mfma_f32_16x16x32_bf16 v[108:111], v[180:183], v[196:199], v[108:111]
	v_mfma_f32_16x16x32_bf16 v[96:99], v[160:163], v[204:207], v[96:99]
	v_mfma_f32_16x16x32_bf16 v[92:95], v[180:183], v[204:207], v[92:95]
	v_mfma_f32_16x16x32_bf16 v[76:79], v[160:163], v[224:227], v[76:79]
	v_mfma_f32_16x16x32_bf16 v[72:75], v[180:183], v[224:227], v[72:75]
	v_mfma_f32_16x16x32_bf16 v[124:127], v[176:179], v[192:195], v[124:127]
	v_mfma_f32_16x16x32_bf16 v[128:131], v[184:187], v[192:195], v[128:131]
	v_mfma_f32_16x16x32_bf16 v[112:115], v[176:179], v[200:203], v[112:115]
	v_mfma_f32_16x16x32_bf16 v[108:111], v[184:187], v[200:203], v[108:111]
	v_mfma_f32_16x16x32_bf16 v[96:99], v[176:179], v[218:221], v[96:99]
	v_mfma_f32_16x16x32_bf16 v[92:95], v[184:187], v[218:221], v[92:95]
	v_mfma_f32_16x16x32_bf16 v[76:79], v[176:179], v[228:231], v[76:79]
	v_mfma_f32_16x16x32_bf16 v[72:75], v[184:187], v[228:231], v[72:75]
	s_setprio 0
	s_barrier
	s_add_i32 s20, 0, 0x1c000
	s_add_i32 s21, s22, s28
	v_add_u32_e32 v169, s20, v158
	v_lshl_add_u64 v[164:165], v[164:165], 0, s[88:89]
	s_mov_b32 m0, s21
	ds_read_b128 v[232:235], v169
	ds_read_b128 v[236:239], v169 offset:1024
	ds_read_b128 v[240:243], v169 offset:2048
	ds_read_b128 v[244:247], v169 offset:3072
	global_load_lds_dwordx4 v[164:165], off
	v_lshl_add_u64 v[164:165], v[248:249], 0, s[88:89]
	s_add_i32 m0, s21, 0x2000
	s_nop 0
	global_load_lds_dwordx4 v[164:165], off
	s_waitcnt vmcnt(10)
	s_barrier
	s_waitcnt lgkmcnt(0)
	s_setprio 1
	s_waitcnt lgkmcnt(0)
	v_mfma_f32_16x16x32_bf16 v[120:123], v[232:235], v[188:191], v[120:123]
	v_mfma_f32_16x16x32_bf16 v[116:119], v[240:243], v[188:191], v[116:119]
	v_mfma_f32_16x16x32_bf16 v[104:107], v[232:235], v[196:199], v[104:107]
	v_mfma_f32_16x16x32_bf16 v[100:103], v[240:243], v[196:199], v[100:103]
	v_mfma_f32_16x16x32_bf16 v[88:91], v[232:235], v[204:207], v[88:91]
	v_mfma_f32_16x16x32_bf16 v[84:87], v[240:243], v[204:207], v[84:87]
	v_mfma_f32_16x16x32_bf16 v[68:71], v[232:235], v[224:227], v[68:71]
	v_mfma_f32_16x16x32_bf16 v[64:67], v[240:243], v[224:227], v[64:67]
	v_mfma_f32_16x16x32_bf16 v[120:123], v[236:239], v[192:195], v[120:123]
	v_mfma_f32_16x16x32_bf16 v[116:119], v[244:247], v[192:195], v[116:119]
	v_mfma_f32_16x16x32_bf16 v[104:107], v[236:239], v[200:203], v[104:107]
	v_mfma_f32_16x16x32_bf16 v[100:103], v[244:247], v[200:203], v[100:103]
	v_mfma_f32_16x16x32_bf16 v[88:91], v[236:239], v[218:221], v[88:91]
	v_mfma_f32_16x16x32_bf16 v[84:87], v[244:247], v[218:221], v[84:87]
	v_mfma_f32_16x16x32_bf16 v[68:71], v[236:239], v[228:231], v[68:71]
	v_mfma_f32_16x16x32_bf16 v[64:67], v[244:247], v[228:231], v[64:67]
	s_setprio 0
	s_mov_b32 m0, s36
	v_lshl_add_u64 v[164:165], v[250:251], 0, s[88:89]
	s_barrier
	ds_read_b128 v[188:191], v159 offset:49152
	ds_read_b128 v[192:195], v159 offset:50176
	ds_read_b128 v[196:199], v159 offset:51200
	ds_read_b128 v[200:203], v159 offset:52224
	ds_read_b128 v[204:207], v159 offset:53248
	ds_read_b128 v[218:221], v159 offset:54272
	ds_read_b128 v[224:227], v159 offset:55296
	ds_read_b128 v[228:231], v159 offset:56320
	global_load_lds_dwordx4 v[164:165], off
	v_lshl_add_u64 v[164:165], v[210:211], 0, s[88:89]
	s_mov_b32 m0, s37
	s_nop 0
	global_load_lds_dwordx4 v[164:165], off
	s_barrier
	s_waitcnt lgkmcnt(0)
	s_setprio 1
	s_waitcnt lgkmcnt(0)
	v_mfma_f32_16x16x32_bf16 v[60:63], v[160:163], v[188:191], v[60:63]
	v_mfma_f32_16x16x32_bf16 v[56:59], v[180:183], v[188:191], v[56:59]
	v_mfma_f32_16x16x32_bf16 v[44:47], v[160:163], v[196:199], v[44:47]
	v_mfma_f32_16x16x32_bf16 v[40:43], v[180:183], v[196:199], v[40:43]
	v_mfma_f32_16x16x32_bf16 v[28:31], v[160:163], v[204:207], v[28:31]
	v_mfma_f32_16x16x32_bf16 v[24:27], v[180:183], v[204:207], v[24:27]
	v_mfma_f32_16x16x32_bf16 v[12:15], v[160:163], v[224:227], v[12:15]
	v_mfma_f32_16x16x32_bf16 v[8:11], v[180:183], v[224:227], v[8:11]
	v_mfma_f32_16x16x32_bf16 v[60:63], v[176:179], v[192:195], v[60:63]
	v_mfma_f32_16x16x32_bf16 v[56:59], v[184:187], v[192:195], v[56:59]
	v_mfma_f32_16x16x32_bf16 v[44:47], v[176:179], v[200:203], v[44:47]
	v_mfma_f32_16x16x32_bf16 v[40:43], v[184:187], v[200:203], v[40:43]
	v_mfma_f32_16x16x32_bf16 v[28:31], v[176:179], v[218:221], v[28:31]
	v_mfma_f32_16x16x32_bf16 v[24:27], v[184:187], v[218:221], v[24:27]
	v_mfma_f32_16x16x32_bf16 v[12:15], v[176:179], v[228:231], v[12:15]
	v_mfma_f32_16x16x32_bf16 v[8:11], v[184:187], v[228:231], v[8:11]
	s_setprio 0
	s_barrier
	s_add_i32 s20, s20, s28
	v_lshl_add_u64 v[160:161], v[170:171], 0, s[88:89]
	s_mov_b32 m0, s20
	s_nop 0
	global_load_lds_dwordx4 v[160:161], off
	v_lshl_add_u64 v[160:161], v[172:173], 0, s[88:89]
	s_add_i32 m0, s20, 0x2000
	s_nop 0
	global_load_lds_dwordx4 v[160:161], off
	s_waitcnt vmcnt(10)
	s_barrier
	s_setprio 1
	v_mfma_f32_16x16x32_bf16 v[52:55], v[232:235], v[188:191], v[52:55]
	v_mfma_f32_16x16x32_bf16 v[48:51], v[240:243], v[188:191], v[48:51]
	v_mfma_f32_16x16x32_bf16 v[36:39], v[232:235], v[196:199], v[36:39]
	v_mfma_f32_16x16x32_bf16 v[32:35], v[240:243], v[196:199], v[32:35]
	v_mfma_f32_16x16x32_bf16 v[20:23], v[232:235], v[204:207], v[20:23]
	v_mfma_f32_16x16x32_bf16 v[16:19], v[240:243], v[204:207], v[16:19]
	v_mfma_f32_16x16x32_bf16 v[4:7], v[232:235], v[224:227], v[4:7]
	v_mfma_f32_16x16x32_bf16 v[0:3], v[240:243], v[224:227], v[0:3]
	v_mfma_f32_16x16x32_bf16 v[52:55], v[236:239], v[192:195], v[52:55]
	v_mfma_f32_16x16x32_bf16 v[48:51], v[244:247], v[192:195], v[48:51]
	v_mfma_f32_16x16x32_bf16 v[36:39], v[236:239], v[200:203], v[36:39]
	v_mfma_f32_16x16x32_bf16 v[32:35], v[244:247], v[200:203], v[32:35]
	v_mfma_f32_16x16x32_bf16 v[20:23], v[236:239], v[218:221], v[20:23]
	v_mfma_f32_16x16x32_bf16 v[16:19], v[244:247], v[218:221], v[16:19]
	v_mfma_f32_16x16x32_bf16 v[4:7], v[236:239], v[228:231], v[4:7]
	v_mfma_f32_16x16x32_bf16 v[0:3], v[244:247], v[228:231], v[0:3]
	s_setprio 0
	s_add_u32 s44, s44, 0x100
	s_addc_u32 s45, s45, 0
	s_add_u32 s18, s18, 0x100
	s_addc_u32 s19, s19, 0
	s_mov_b32 s20, s46
	s_add_i32 s46, s20, 2
	s_add_u32 s22, s18, 0x80
	s_addc_u32 s21, s19, 0
	s_cmp_ge_i32 s20, s38
	s_barrier
	s_cbranch_scc0 .Lp2_rot
